# v24 + one static s_setprio 1 for waves 4-7 (second wave of each SIMD) for the duration of every attention unit, reset at the queue loop head
# speedup vs baseline: 1.0043x; 1.0028x over previous
; __device__ __forceinline__ unsigned xb_xcc_id() { return (unsigned)__builtin_amdgcn_s_getreg((3 << 11) | 20) & 0xFu; }
; __device__ __forceinline__ void ph_mix(int l, LAS unsigned char* lds, unsigned char* lds_raw) {
;     ...
;     for (;;) {
;         PH_PRE
;         const int x0 = (int)(xb_xcc_id() & 7u);
;         unsigned* qbase = (unsigned*)(ws + WS_CTL) + CW_Q + 64 * (l * 8);
;         if (tid == 0) { int found = -1;
;             for (int dx = 0; dx < 8; ++dx) { const int y = (x0 + dx) & 7; unsigned* qp = qbase + 64 * y;
;                 if (__hip_atomic_load(qp, __ATOMIC_RELAXED, __HIP_MEMORY_SCOPE_AGENT) >= (unsigned)nq) continue;
;                 const int idx = (int)__hip_atomic_fetch_add(qp, 1u, __ATOMIC_RELAXED, __HIP_MEMORY_SCOPE_AGENT);
;                 if (idx < nq) { found = y * 256 + idx; break; } }
;             *s_item = found; }
;         __syncthreads(); const int itq = __builtin_amdgcn_readfirstlane(*s_item); __syncthreads();
;         if (itq < 0) break;
.LBB0_1311:
.LBB0_1312:
	s_setprio 0
	s_mov_b64 s[2:3], s[0:1]
	s_waitcnt vmcnt(0)
	v_mov_b32_e32 v0, v206
	s_mov_b32 s4, s8
	s_load_dwordx2 s[68:69], s[2:3], 0xd0
	s_getreg_b32 s10, hwreg(HW_REG_XCC_ID, 0, 4)
	v_cmp_eq_u32_e32 vcc, 0, v0
	s_and_saveexec_b64 s[2:3], vcc
	s_cbranch_execz .LBB0_1373
	s_waitcnt lgkmcnt(0)
	s_add_u32 s4, s68, s6
	s_addc_u32 s5, s69, s7
	s_and_b32 s24, s10, 7
	s_lshl_b32 s12, s24, 8
	v_mov_b32_e32 v0, s12
	global_load_dword v0, v0, s[4:5] offset:256 sc1
	s_add_u32 s12, s4, s12
	s_addc_u32 s13, s5, 0
	s_waitcnt vmcnt(0)
	v_cmp_le_u32_e32 vcc, s31, v0
	s_cbranch_vccnz .LBB0_1317
	s_mov_b64 s[16:17], exec
	v_mbcnt_lo_u32_b32 v0, s16, 0
	v_mbcnt_hi_u32_b32 v0, s17, v0
	v_cmp_eq_u32_e32 vcc, 0, v0
	s_and_saveexec_b64 s[14:15], vcc
	s_cbranch_execz .LBB0_1316
	s_bcnt1_i32_b64 s16, s[16:17]
	v_mov_b32_e32 v1, s16
	global_atomic_add v1, v161, v1, s[12:13] offset:256 sc0

; #define SWAIT() asm volatile("s_waitcnt vmcnt(0)" ::: "memory")
; __device__ __forceinline__ void attn_unit(const bf16_t* __restrict__ Qb, const bf16_t* __restrict__ Kh, const bf16_t* __restrict__ Vh, bf16_t* __restrict__ Ob, int seq, char* lds) {
;     const int tid = get_tid(), wid = tid >> 6, lane = tid & 63, r32 = lane & 31, hi = lane >> 5;
;     char* V_lds = lds; char* K_lds = lds + 2 * SHM_V;
;     float* ws = (float*)(lds + 2 * SHM_V + 2 * SHM_K) + wid * 64; float* li_l = ws; float* al_l = ws + 32;
;     float m_reg = -1e30f, l_reg = 0; f32x16 o[4] = {}; bf16x8 qr[QREG > 0 ? QREG : 1];
;     char* qrl = lds + 2 * SHM_V + 2 * SHM_K + 2048 + wid * (12 - QREG) * 1024 + lane * 16;
;     const bf16_t* Qw = Qb + (size_t)(wid * QBLK + r32) * QLD + hi * 8;
; #pragma unroll
;     for (int d0 = 0; d0 < QREG; ++d0) qr[d0] = *reinterpret_cast<const bf16x8*>(Qw + d0 * 16);
; #pragma unroll
;     for (int d0 = 0; d0 < 12 - QREG; ++d0) *reinterpret_cast<bf16x8*>(qrl + d0 * 1024) = *reinterpret_cast<const bf16x8*>(Qw + (QREG + d0) * 16);
;     const int sr = tid >> 4, sc = (tid & 15) * 8, vst0 = v_st(sr, sc), vst1 = v_st(32 + sr, sc);
;     const int kr0 = tid / 24, kc0 = tid % 24, kr1 = (tid + 512) / 24, kc1 = (tid + 512) % 24, kr2 = (tid + 1024) / 24, kc2 = (tid + 1024) % 24;
;     const int vb0 = (int)(uintptr_t)V_lds + v_rd_base(lane);
;     bf16x8 vs0, vs1, ks0, ks1, ks2;
;     ...
;     f32x16 pA0, pA1, pB0, pB1; float mnA, mnB, alA, alB; bf16x8 pa0, pa1, pa2, pa3; const int NT = seq / KVBLK;
;     SLOAD(0); SWAIT(); SWRITE(0); __syncthreads();
; __device__ __forceinline__ void ph_mix(int l, LAS unsigned char* lds, unsigned char* lds_raw) {
;     ...
;         const int y = itq >> 8, idx = itq & 255;
;         if (idx < 16) gla_scan_item(a, (y * 4 + (idx >> 2)) * 4 + (idx & 3), lds);
;         else { int u = idx - 16, gi, qb;
;             if (u < 64) { gi = y * 8 + (u >> 3); qb = 1 + (u & 7); } else { gi = y * 8 + (u - 64); qb = 0; }
;             const int b = gi >> 4, h = gi & 15;
;             const bf16_t* Qb = (const bf16_t*)(ws + WS_Q); const bf16_t* KB = (const bf16_t*)(ws + WS_KB); const bf16_t* VB = (const bf16_t*)(ws + WS_VB); bf16_t* GMB = (bf16_t*)(ws + WS_GMB);
;             att::attn_unit(Qb + (size_t)(b * SB + qb * 256) * QLD + h * 192, KB + (size_t)(b * SB) * KLD + h * 192, VB + (size_t)(b * SB) * VLD + h * 128,
.LBB0_1379:
	s_lshr_b32 s2, s4, 4
	s_mul_i32 s14, s2, 0x900
	s_lshl_b32 s3, s13, 8
	s_add_i32 s10, s14, s3
	s_and_b32 s43, s4, 15
	s_mul_i32 s4, s10, 0x1800
	s_mul_hi_u32 s3, s10, 0x1800
	s_add_u32 s4, s68, s4
	s_addc_u32 s3, s69, s3
	s_mul_i32 s18, s43, 0x180
	s_add_u32 s4, s4, s18
	s_addc_u32 s3, s3, 0
	v_readfirstlane_b32 s16, v206
	s_cmpk_lt_u32 s16, 0x100
	s_cbranch_scc1 .Lmy_prio_skip
	s_setprio 1
.Lmy_prio_skip:
	v_mov_b32_e32 v56, v206
	s_add_u32 s16, s4, 0x1c800000
	s_addc_u32 s17, s3, 0
	v_ashrrev_i32_e32 v64, 6, v56
	v_and_b32_e32 v159, 31, v56
	v_lshlrev_b32_e32 v148, 5, v64
	v_or_b32_e32 v2, v148, v159
	v_mov_b64_e32 v[0:1], s[16:17]
	v_bfe_u32 v172, v56, 5, 1
	v_mad_i64_i32 v[0:1], s[16:17], v2, s41, v[0:1]
	v_lshlrev_b32_e32 v160, 4, v172
	s_mov_b32 s16, 0x2aaaaaab
	v_lshl_add_u64 v[58:59], v[0:1], 0, v[160:161]
	v_mul_hi_i32 v0, v56, s16
	s_mul_i32 s4, s2, 0xd80000
	v_lshrrev_b32_e32 v1, 31, v0
	v_ashrrev_i32_e32 v0, 2, v0
	s_mul_hi_u32 s5, s14, 0x1800
	s_add_u32 s2, s68, s4
	v_add_u32_e32 v57, v0, v1
	s_addc_u32 s3, s69, s5
	v_mul_lo_u32 v0, v57, 24
	s_add_u32 s2, s2, s18
	v_sub_u32_e32 v66, v56, v0
	v_add_u32_e32 v0, 0x200, v56
	s_addc_u32 s3, s3, 0
	v_mul_hi_i32 v1, v0, s16
	s_mov_b32 s15, s11
	s_add_u32 s2, s2, 0x1fe00000
	v_lshrrev_b32_e32 v3, 31, v1
	v_ashrrev_i32_e32 v1, 2, v1
	s_addc_u32 s3, s3, 0
	s_lshl_b64 s[70:71], s[14:15], 12
	v_add_u32_e32 v86, v1, v3
	s_add_u32 s14, s68, s70
	v_mul_lo_u32 v1, v86, 24
	s_addc_u32 s15, s69, s71
	s_lshl_b32 s48, s43, 7
	s_lshl_b32 s55, s43, 8
	v_sub_u32_e32 v67, v0, v1
	v_add_u32_e32 v0, 0x400, v56
	s_add_u32 s14, s14, s55
	global_load_dwordx4 v[4:7], v[58:59], off offset:192
	global_load_dwordx4 v[8:11], v[58:59], off offset:224
	global_load_dwordx4 v[12:15], v[58:59], off offset:256
	global_load_dwordx4 v[16:19], v[58:59], off offset:288
	global_load_dwordx4 v[20:23], v[58:59], off offset:320
	global_load_dwordx4 v[24:27], v[58:59], off offset:352
	v_mul_hi_i32 v1, v0, s16
	s_addc_u32 s15, s15, 0
	v_ashrrev_i32_e32 v60, 4, v56
	v_lshrrev_b32_e32 v3, 31, v1
	v_ashrrev_i32_e32 v1, 2, v1
	s_add_u32 s14, s14, 0x23400000
	v_lshlrev_b32_e32 v65, 3, v56
	v_add_u32_e32 v87, v1, v3
	v_ashrrev_i32_e32 v61, 31, v60
	s_addc_u32 s15, s15, 0
	v_and_b32_e32 v2, 0x78, v65
	v_add_u32_e32 v62, 32, v60
	v_mul_lo_u32 v1, v87, 24
	v_lshlrev_b64 v[48:49], 12, v[60:61]
	v_sub_u32_e32 v68, v0, v1
	v_lshl_add_u64 v[0:1], s[14:15], 0, v[48:49]
	v_lshlrev_b32_e32 v28, 1, v2
	v_mov_b32_e32 v29, v161
	v_ashrrev_i32_e32 v63, 31, v62
	v_lshl_add_u64 v[2:3], v[0:1], 0, v[28:29]
	v_lshlrev_b64 v[0:1], 12, v[62:63]
	v_lshl_add_u64 v[0:1], s[14:15], 0, v[0:1]
	v_lshl_add_u64 v[0:1], v[0:1], 0, v[28:29]
	v_lshlrev_b32_e32 v36, 3, v66
	v_lshlrev_b32_e32 v40, 3, v67
	global_load_dwordx4 v[28:31], v[2:3], off
	global_load_dwordx4 v[32:35], v[0:1], off
	v_ashrrev_i32_e32 v37, 31, v36
	v_mov_b64_e32 v[0:1], s[2:3]
	v_ashrrev_i32_e32 v41, 31, v40
	v_lshlrev_b32_e32 v44, 3, v68
	v_mad_i64_i32 v[38:39], s[2:3], v57, s41, v[0:1]
	v_lshlrev_b64 v[50:51], 1, v[36:37]
	v_mad_i64_i32 v[42:43], s[2:3], v86, s41, v[0:1]
	v_lshlrev_b64 v[52:53], 1, v[40:41]
	v_ashrrev_i32_e32 v45, 31, v44
	v_lshl_add_u64 v[36:37], v[38:39], 0, v[50:51]
	v_lshl_add_u64 v[40:41], v[42:43], 0, v[52:53]
	v_mad_i64_i32 v[46:47], s[2:3], v87, s41, v[0:1]
	v_lshlrev_b64 v[54:55], 1, v[44:45]
	global_load_dwordx4 v[36:39], v[36:37], off
	v_lshl_add_u64 v[44:45], v[46:47], 0, v[54:55]
	global_load_dwordx4 v[40:43], v[40:41], off
	s_nop 0
	global_load_dwordx4 v[44:47], v[44:45], off
	s_nop 0
	global_load_dwordx4 v[116:119], v[58:59], off
	global_load_dwordx4 v[112:115], v[58:59], off offset:32
	global_load_dwordx4 v[108:111], v[58:59], off offset:64
	global_load_dwordx4 v[104:107], v[58:59], off offset:96
	global_load_dwordx4 v[100:103], v[58:59], off offset:128
	global_load_dwordx4 v[96:99], v[58:59], off offset:160
	s_cmp_eq_u32 s13, 0
	s_cselect_b32 s51, 4, 36
	v_and_b32_e32 v88, 63, v56
	v_mul_lo_u32 v61, v64, s41
	s_add_i32 s2, 0, 0x18800
	v_lshlrev_b32_e32 v82, 4, v88
	v_add_u32_e32 v58, s2, v61
	v_add_u32_e32 v177, v58, v82
	s_waitcnt vmcnt(16)
	ds_write_b128 v177, v[4:7]
	s_waitcnt vmcnt(15)
	ds_write_b128 v177, v[8:11] offset:1024
	s_waitcnt vmcnt(14)
	ds_write_b128 v177, v[12:15] offset:2048
	s_waitcnt vmcnt(13)
	ds_write_b128 v177, v[16:19] offset:3072
	s_waitcnt vmcnt(12)
	ds_write_b128 v177, v[20:23] offset:4096
	s_waitcnt vmcnt(11)
	ds_write_b128 v177, v[24:27] offset:5120
	v_and_b32_e32 v4, 0xfffff0, v60
	v_lshlrev_b32_e32 v5, 1, v60
	v_and_b32_e32 v9, 0xfffff0, v62
	v_lshlrev_b32_e32 v10, 1, v62
	v_and_or_b32 v4, v5, 8, v4
	v_and_or_b32 v9, v10, 8, v9
	v_lshrrev_b32_e32 v5, 1, v60
	v_lshrrev_b32_e32 v4, 1, v4
	v_bfe_u32 v6, v65, 5, 2
	v_and_b32_e32 v7, 3, v60
	v_lshrrev_b32_e32 v9, 1, v9
	v_or_b32_e32 v4, v4, v6
	v_and_or_b32 v5, v5, 4, v7
	v_lshlrev_b32_e32 v7, 4, v56
	v_or_b32_e32 v6, v9, v6
	v_lshlrev_b32_e32 v4, 9, v4
	v_lshlrev_b32_e32 v5, 6, v5
	v_and_b32_e32 v8, 48, v7
	v_lshlrev_b32_e32 v6, 9, v6
	v_or3_b32 v4, v4, v5, v8
	v_or3_b32 v5, v6, v5, v8
	v_add_u32_e32 v178, 0, v4
	v_add_u32_e32 v179, 0, v5
	v_lshlrev_b32_e32 v4, 9, v57
	v_bitop3_b32 v5, v57, v66, 15 bitop3:0x6c
	v_lshl_add_u32 v89, v5, 4, v4
	v_lshlrev_b32_e32 v4, 9, v86
	v_bitop3_b32 v5, v86, v67, 15 bitop3:0x6c
	v_lshl_add_u32 v90, v5, 4, v4
	v_lshlrev_b32_e32 v4, 9, v87
	v_bitop3_b32 v5, v87, v68, 15 bitop3:0x6c
	v_lshlrev_b32_e32 v83, 9, v159
	v_and_b32_e32 v84, 0xf0, v7
	v_lshl_add_u32 v91, v5, 4, v4
	v_bitop3_b32 v183, v160, v83, v84 bitop3:0xde
	v_add_u32_e32 v180, 0, v89
	v_add_u32_e32 v181, 0, v90
	v_add_u32_e32 v182, 0, v91
	v_add_u32_e32 v184, 0, v183
	s_waitcnt vmcnt(0)
	s_waitcnt vmcnt(10)
	ds_write_b128 v178, v[28:31]
	s_waitcnt vmcnt(9)
	ds_write_b128 v179, v[32:35]
	s_waitcnt vmcnt(8)
	ds_write_b128 v180, v[36:39] offset:32768
	s_add_i32 s2, 0, 0x18000
	s_waitcnt vmcnt(7)
	ds_write_b128 v181, v[40:43] offset:32768
	s_waitcnt vmcnt(6)
	ds_write_b128 v182, v[44:47] offset:32768
	s_waitcnt lgkmcnt(0)
	s_barrier
; #define SWRITE(b) do { *(bf16x8*)(V_lds + (b) * SHM_V + vst0) = vs0; *(bf16x8*)(V_lds + (b) * SHM_V + vst1) = vs1; \
;     *(bf16x8*)(K_lds + (b) * SHM_K + KSWZ(kr0, kc0 * 16)) = ks0; *(bf16x8*)(K_lds + (b) * SHM_K + KSWZ(kr1, kc1 * 16)) = ks1; *(bf16x8*)(K_lds + (b) * SHM_K + KSWZ(kr2, kc2 * 16)) = ks2; } while (0)
; #define SWAIT() asm volatile("s_waitcnt vmcnt(0)" ::: "memory")
; __device__ __forceinline__ void qkt(f32x16& p0, f32x16& p1, const char* Ks, const bf16x8* qr, const char* qrl, int r32, int hi) {
;     p0 = f32x16{}; p1 = f32x16{};
; #pragma unroll
;     for (int d0 = 0; d0 < 12; ++d0) { const int cb = (d0 * 16 + hi * 8) * 2;
;         const bf16x8 b0 = *reinterpret_cast<const bf16x8*>(Ks + KSWZ(r32, cb));
;         const bf16x8 b1 = *reinterpret_cast<const bf16x8*>(Ks + KSWZ(32 + r32, cb));
;         const bf16x8 qq = d0 < QREG ? qr[d0 < QREG ? d0 : 0] : *reinterpret_cast<const bf16x8*>(qrl + (d0 - QREG) * 1024);
;         p0 = __builtin_amdgcn_mfma_f32_32x32x16_bf16(b0, qq, p0, 0, 0, 0);
;         p1 = __builtin_amdgcn_mfma_f32_32x32x16_bf16(b1, qq, p1, 0, 0, 0); }
; __device__ __forceinline__ void attn_unit(const bf16_t* __restrict__ Qb, const bf16_t* __restrict__ Kh, const bf16_t* __restrict__ Vh, bf16_t* __restrict__ Ob, int seq, char* lds) {
;     ...
;     SLOAD(0); SWAIT(); SWRITE(0); __syncthreads();
;     qkt(pA0, pA1, K_lds, qr, qrl, r32, hi); partialSM(pA0, pA1, m_reg, mnA, alA);
;     SLOAD(KVBLK);
;     SWAIT(); SWRITE(1); __syncthreads();
	ds_read_b128 v[4:7], v184 offset:32768
	ds_read_b128 v[8:11], v184 offset:49152
	s_waitcnt vmcnt(5) lgkmcnt(1)
	v_mfma_f32_32x32x16_bf16 v[16:31], v[4:7], v[116:119], 0
	v_or_b32_e32 v4, 32, v160
	v_bitop3_b32 v185, v4, v83, v84 bitop3:0xde
	v_add_u32_e32 v186, 0, v185
	v_lshlrev_b32_e32 v85, 3, v88
	s_mov_b32 s13, s12
	s_cmp_lg_u32 0, -1
	s_mov_b32 s14, s12
	s_waitcnt lgkmcnt(0)
	v_mfma_f32_32x32x16_bf16 v[32:47], v[8:11], v[116:119], 0
	ds_read_b128 v[4:7], v186 offset:32768
	ds_read_b128 v[8:11], v186 offset:49152
	s_mov_b32 s15, s12
	s_mov_b32 s16, s12
	s_mov_b32 s17, s12
	s_mov_b32 s18, s12
	s_mov_b32 s19, s12
	s_mov_b32 s20, s12
	s_waitcnt vmcnt(4) lgkmcnt(1)
	v_mfma_f32_32x32x16_bf16 v[16:31], v[4:7], v[112:115], v[16:31]
	v_or_b32_e32 v4, 64, v160
	v_bitop3_b32 v187, v4, v83, v84 bitop3:0xde
	v_add_u32_e32 v188, 0, v187
	s_mov_b32 s21, s12
	s_mov_b32 s22, s12
	s_mov_b32 s23, s12
	s_mov_b32 s24, s12
	s_waitcnt lgkmcnt(0)
	v_mfma_f32_32x32x16_bf16 v[32:47], v[8:11], v[112:115], v[32:47]
	ds_read_b128 v[4:7], v188 offset:32768
	ds_read_b128 v[8:11], v188 offset:49152
	s_mov_b32 s25, s12
	s_mov_b32 s26, s12
	s_mov_b32 s27, s12
	s_cselect_b32 s30, 0, 0
	v_lshl_add_u64 v[156:157], v[48:49], 0, s[70:71]
	s_mov_b32 s52, 2
	s_waitcnt vmcnt(3) lgkmcnt(1)
	v_mfma_f32_32x32x16_bf16 v[16:31], v[4:7], v[108:111], v[16:31]
	v_or_b32_e32 v4, 0x60, v160
	v_bitop3_b32 v189, v4, v83, v84 bitop3:0xde
	v_add_u32_e32 v190, 0, v189
	v_mov_b32_e32 v174, 0
	s_waitcnt lgkmcnt(0)
	v_mfma_f32_32x32x16_bf16 v[32:47], v[8:11], v[108:111], v[32:47]
	ds_read_b128 v[4:7], v190 offset:32768
	ds_read_b128 v[8:11], v190 offset:49152
	s_waitcnt vmcnt(2) lgkmcnt(1)
	v_mfma_f32_32x32x16_bf16 v[16:31], v[4:7], v[104:107], v[16:31]
	v_or_b32_e32 v4, 0x80, v160
	v_bitop3_b32 v191, v4, v83, v84 bitop3:0xde
	v_add_u32_e32 v192, 0, v191
	s_waitcnt lgkmcnt(0)
	v_mfma_f32_32x32x16_bf16 v[32:47], v[8:11], v[104:107], v[32:47]
	ds_read_b128 v[4:7], v192 offset:32768
	ds_read_b128 v[8:11], v192 offset:49152
	s_waitcnt vmcnt(1) lgkmcnt(1)
	v_mfma_f32_32x32x16_bf16 v[16:31], v[4:7], v[100:103], v[16:31]
	v_or_b32_e32 v4, 0xa0, v160
	v_bitop3_b32 v193, v4, v83, v84 bitop3:0xde
	v_add_u32_e32 v194, 0, v193
	s_waitcnt lgkmcnt(0)
	v_mfma_f32_32x32x16_bf16 v[32:47], v[8:11], v[100:103], v[32:47]
	ds_read_b128 v[4:7], v194 offset:32768
	ds_read_b128 v[8:11], v194 offset:49152
	s_waitcnt vmcnt(0) lgkmcnt(1)
	v_mfma_f32_32x32x16_bf16 v[16:31], v[4:7], v[96:99], v[16:31]
	v_or_b32_e32 v4, 0xc0, v160
	v_bitop3_b32 v195, v4, v83, v84 bitop3:0xde
	v_add_u32_e32 v196, 0, v195
	s_waitcnt lgkmcnt(0)
	v_mfma_f32_32x32x16_bf16 v[32:47], v[8:11], v[96:99], v[32:47]
	ds_read_b128 v[4:7], v196 offset:32768
	ds_read_b128 v[8:11], v177
	ds_read_b128 v[12:15], v196 offset:49152
	ds_read_b128 v[58:61], v177 offset:1024
	s_waitcnt lgkmcnt(2)
	v_mfma_f32_32x32x16_bf16 v[16:31], v[4:7], v[8:11], v[16:31]
	v_or_b32_e32 v4, 0xe0, v160
	v_bitop3_b32 v197, v4, v83, v84 bitop3:0xde
	v_add_u32_e32 v198, 0, v197
	s_waitcnt lgkmcnt(1)
	v_mfma_f32_32x32x16_bf16 v[32:47], v[12:15], v[8:11], v[32:47]
	ds_read_b128 v[4:7], v198 offset:32768
	ds_read_b128 v[8:11], v198 offset:49152
	s_waitcnt lgkmcnt(1)
	v_mfma_f32_32x32x16_bf16 v[16:31], v[4:7], v[58:61], v[16:31]
	v_or_b32_e32 v4, 0x100, v160
	v_bitop3_b32 v199, v4, v83, v84 bitop3:0xde
	v_add_u32_e32 v200, 0, v199
	s_waitcnt lgkmcnt(0)
	v_mfma_f32_32x32x16_bf16 v[32:47], v[8:11], v[58:61], v[32:47]
	ds_read_b128 v[4:7], v200 offset:32768
	ds_read_b128 v[8:11], v177 offset:2048
	ds_read_b128 v[12:15], v200 offset:49152
	ds_read_b128 v[58:61], v177 offset:3072
	s_waitcnt lgkmcnt(2)
	v_mfma_f32_32x32x16_bf16 v[16:31], v[4:7], v[8:11], v[16:31]
	v_and_b32_e32 v4, 0x3fffffc0, v56
	v_lshl_add_u32 v149, v4, 2, s2
	v_or_b32_e32 v4, 0x120, v160
	s_mov_b32 s2, 0x40000
	v_bitop3_b32 v201, v4, v83, v84 bitop3:0xde
	v_add_u32_e32 v202, 0, v201
	ds_read_b128 v[4:7], v202 offset:32768
	s_waitcnt lgkmcnt(2)
	v_mfma_f32_32x32x16_bf16 v[32:47], v[12:15], v[8:11], v[32:47]
	v_add_co_u32_e32 v8, vcc, s2, v2
	s_mov_b32 s2, 0x60000
	s_nop 0
	v_addc_co_u32_e32 v9, vcc, 0, v3, vcc
	v_add_co_u32_e32 v2, vcc, s2, v2
	s_waitcnt lgkmcnt(0)
	v_mfma_f32_32x32x16_bf16 v[16:31], v[4:7], v[58:61], v[16:31]
	v_addc_co_u32_e32 v3, vcc, 0, v3, vcc
	global_load_dwordx4 v[62:65], v[8:9], off
	global_load_dwordx4 v[66:69], v[2:3], off
	v_add_u32_e32 v2, 64, v57
	v_mad_i64_i32 v[2:3], s[2:3], v2, s41, v[0:1]
	v_add_u32_e32 v8, 64, v86
	v_lshl_add_u64 v[2:3], v[2:3], 0, v[50:51]
	v_mad_i64_i32 v[8:9], s[2:3], v8, s41, v[0:1]
	v_lshl_add_u64 v[8:9], v[8:9], 0, v[52:53]
	global_load_dwordx4 v[70:73], v[2:3], off
	global_load_dwordx4 v[74:77], v[8:9], off
	v_add_u32_e32 v2, 64, v87
	v_mad_i64_i32 v[0:1], s[2:3], v2, s41, v[0:1]
	v_lshl_add_u64 v[0:1], v[0:1], 0, v[54:55]
	global_load_dwordx4 v[78:81], v[0:1], off
	v_and_b32_e32 v0, 0xc0, v82
	v_and_or_b32 v8, v85, 24, v0
	ds_read_b128 v[0:3], v202 offset:49152
	v_lshlrev_b32_e32 v4, 1, v56
	v_and_b32_e32 v9, 32, v4
	v_or_b32_e32 v4, 0x140, v160
	v_bitop3_b32 v203, v4, v83, v84 bitop3:0xde
	v_add_u32_e32 v204, 0, v203
	ds_read_b128 v[4:7], v204 offset:32768
	s_waitcnt lgkmcnt(1)
; #define SWRITE(b) do { *(bf16x8*)(V_lds + (b) * SHM_V + vst0) = vs0; *(bf16x8*)(V_lds + (b) * SHM_V + vst1) = vs1; \
;     *(bf16x8*)(K_lds + (b) * SHM_K + KSWZ(kr0, kc0 * 16)) = ks0; *(bf16x8*)(K_lds + (b) * SHM_K + KSWZ(kr1, kc1 * 16)) = ks1; *(bf16x8*)(K_lds + (b) * SHM_K + KSWZ(kr2, kc2 * 16)) = ks2; } while (0)
; #define SWAIT() asm volatile("s_waitcnt vmcnt(0)" ::: "memory")
; __device__ __forceinline__ void partialSM(f32x16& p0, f32x16& p1, float& m_reg, float& mn, float& alpha) {
;     float pmax = p0[0];
; #pragma unroll
;     for (int r = 1; r < 16; ++r) pmax = fmaxf(pmax, p0[r]);
; #pragma unroll
;     for (int r = 0; r < 16; ++r) pmax = fmaxf(pmax, p1[r]);
;     { auto rr = __builtin_amdgcn_permlane32_swap(__float_as_uint(pmax), __float_as_uint(pmax), false, false); pmax = fmaxf(__uint_as_float(rr[0]), __uint_as_float(rr[1])); }
;     if (__builtin_expect(__all(pmax - m_reg <= THR2), 1)) { mn = m_reg; alpha = 1.f; }
;     else { mn = fmaxf(m_reg, pmax); alpha = __builtin_amdgcn_exp2f(m_reg - mn); m_reg = mn; }
; #pragma unroll
;     for (int r = 0; r < 16; ++r) p0[r] = p0[r] - mn;
; #pragma unroll
;     for (int r = 0; r < 16; ++r) p1[r] = p1[r] - mn;
; #pragma unroll
;     for (int r = 0; r < 16; ++r) p0[r] = __builtin_amdgcn_exp2f(p0[r]);
; }
; __device__ __forceinline__ void attn_unit(const bf16_t* __restrict__ Qb, const bf16_t* __restrict__ Kh, const bf16_t* __restrict__ Vh, bf16_t* __restrict__ Ob, int seq, char* lds) {
;     ...
;     SLOAD(0); SWAIT(); SWRITE(0); __syncthreads();
;     qkt(pA0, pA1, K_lds, qr, qrl, r32, hi); partialSM(pA0, pA1, m_reg, mnA, alA);
;     SLOAD(KVBLK);
;     SWAIT(); SWRITE(1); __syncthreads();
	v_mfma_f32_32x32x16_bf16 v[32:47], v[0:3], v[58:61], v[32:47]
	ds_read_b128 v[0:3], v177 offset:4096
	v_and_b32_e32 v10, 0x100, v85
	v_or3_b32 v92, v8, v9, v10
	ds_read_b128 v[8:11], v204 offset:49152
	ds_read_b128 v[58:61], v177 offset:5120
	v_add_u32_e32 v176, s30, v92
	v_cmp_gt_u32_e64 s[2:3], 32, v88
	v_lshl_add_u32 v173, v159, 2, v149
	s_waitcnt lgkmcnt(2)
	v_mfma_f32_32x32x16_bf16 v[16:31], v[4:7], v[0:3], v[16:31]
	v_or_b32_e32 v4, 0x160, v160
	v_bitop3_b32 v205, v4, v83, v84 bitop3:0xde
	v_add_u32_e32 v215, 0, v205
	ds_read_b128 v[4:7], v215 offset:32768
	ds_read_b128 v[82:85], v215 offset:49152
	s_waitcnt vmcnt(0)
	s_waitcnt vmcnt(4)
	ds_write_b128 v178, v[62:65] offset:16384
	s_waitcnt vmcnt(3)
	ds_write_b128 v179, v[66:69] offset:16384
	s_waitcnt lgkmcnt(5)
	v_mfma_f32_32x32x16_bf16 v[32:47], v[8:11], v[0:3], v[32:47]
	s_waitcnt lgkmcnt(3)
	v_mfma_f32_32x32x16_bf16 v[16:31], v[4:7], v[58:61], v[16:31]
	v_mov_b64_e32 v[0:1], s[12:13]
	v_mov_b64_e32 v[2:3], s[14:15]
	v_mov_b64_e32 v[4:5], s[16:17]
	v_mov_b64_e32 v[6:7], s[18:19]
	v_mov_b64_e32 v[8:9], s[20:21]
	v_mov_b64_e32 v[10:11], s[22:23]
	v_mov_b64_e32 v[12:13], s[24:25]
	s_waitcnt lgkmcnt(2)
	v_mfma_f32_32x32x16_bf16 v[32:47], v[82:85], v[58:61], v[32:47]
	s_nop 2
	v_max_f32_e32 v58, v17, v17
	v_max_f32_e32 v59, v16, v16
	v_max_f32_e32 v58, v59, v58
	v_max3_f32 v58, v58, v18, v19
	v_max3_f32 v58, v58, v20, v21
	v_max3_f32 v58, v58, v22, v23
	v_max3_f32 v58, v58, v24, v25
	v_max3_f32 v58, v58, v26, v27
	v_max3_f32 v58, v58, v28, v29
	v_max3_f32 v58, v58, v30, v31
	v_max3_f32 v58, v58, v32, v33
	v_max3_f32 v58, v58, v34, v35
	v_max3_f32 v58, v58, v36, v37
	v_max3_f32 v58, v58, v38, v39
	v_max3_f32 v58, v58, v40, v41
	v_max3_f32 v58, v58, v42, v43
	v_max3_f32 v58, v58, v44, v45
	v_max3_f32 v58, v58, v46, v47
	v_mov_b32_e32 v59, v58
	s_nop 1
	v_permlane32_swap_b32_e32 v58, v59
	v_max_f32_e32 v59, v59, v59
	v_max_f32_e32 v58, v58, v58
	v_max_f32_e32 v58, v58, v59
	v_add_f32_e32 v59, 0x7149f2ca, v58
	v_mov_b64_e32 v[14:15], s[26:27]
	v_cmp_ge_f32_e32 vcc, s62, v59
	s_add_i32 s14, 0, 0x10000
	s_cmp_eq_u64 vcc, exec
	v_max_f32_e32 v58, 0xf149f2ca, v58
	s_cselect_b64 vcc, -1, 0
	v_mov_b32_e32 v59, 0xf149f2ca
	v_cndmask_b32_e32 v158, v58, v59, vcc
	v_sub_f32_e32 v16, v16, v158
	v_exp_f32_e32 v136, v16
	v_sub_f32_e32 v16, v17, v158
	v_exp_f32_e32 v166, v16
	v_sub_f32_e32 v16, v18, v158
	v_exp_f32_e32 v137, v16
	v_sub_f32_e32 v16, v19, v158
	v_exp_f32_e32 v167, v16
	v_sub_f32_e32 v16, v20, v158
	v_exp_f32_e32 v138, v16
	v_sub_f32_e32 v16, v21, v158
	v_exp_f32_e32 v168, v16
	v_sub_f32_e32 v16, v22, v158
	v_exp_f32_e32 v139, v16
	v_sub_f32_e32 v16, v23, v158
	v_exp_f32_e32 v165, v16
	v_sub_f32_e32 v16, v24, v158
	v_exp_f32_e32 v144, v16
	v_sub_f32_e32 v16, v25, v158
	v_exp_f32_e32 v146, v16
	v_sub_f32_e32 v16, v26, v158
	v_exp_f32_e32 v145, v16
	v_sub_f32_e32 v16, v27, v158
	v_exp_f32_e32 v164, v16
	v_sub_f32_e32 v16, v28, v158
	v_exp_f32_e32 v141, v16
	v_sub_f32_e32 v16, v29, v158
	v_exp_f32_e32 v143, v16
	v_sub_f32_e32 v16, v30, v158
	v_exp_f32_e32 v142, v16
	v_sub_f32_e32 v16, v31, v158
	v_exp_f32_e32 v147, v16
	v_mov_b64_e32 v[16:17], s[4:5]
	v_mad_i64_i32 v[18:19], s[4:5], v87, s41, v[16:17]
	v_sub_f32_e32 v132, v32, v158
	v_sub_f32_e32 v32, 0xf149f2ca, v58
	v_mad_u64_u32 v[18:19], s[4:5], s43, v214, v[18:19]
	v_exp_f32_e32 v32, v32
	v_lshl_add_u64 v[150:151], v[18:19], 0, v[54:55]
	v_mad_i64_i32 v[18:19], s[4:5], v86, s41, v[16:17]
	v_mad_i64_i32 v[16:17], s[4:5], v57, s41, v[16:17]
	v_mad_u64_u32 v[16:17], s[4:5], s43, v214, v[16:17]
	v_lshl_add_u64 v[154:155], v[16:17], 0, v[50:51]
	v_and_b32_e32 v16, 15, v56
	v_mad_u64_u32 v[18:19], s[4:5], s43, v214, v[18:19]
	v_lshlrev_b32_e32 v16, 4, v16
	v_sub_f32_e32 v133, v33, v158
	v_sub_f32_e32 v134, v34, v158
	v_sub_f32_e32 v135, v35, v158
	v_sub_f32_e32 v122, v36, v158
	v_sub_f32_e32 v123, v37, v158
	v_sub_f32_e32 v124, v38, v158
	v_sub_f32_e32 v125, v39, v158
	v_sub_f32_e32 v126, v40, v158
	v_sub_f32_e32 v127, v41, v158
	v_sub_f32_e32 v130, v42, v158
	v_sub_f32_e32 v131, v43, v158
	v_sub_f32_e32 v120, v44, v158
	v_sub_f32_e32 v121, v45, v158
	v_sub_f32_e32 v128, v46, v158
	v_sub_f32_e32 v129, v47, v158
	v_cndmask_b32_e64 v219, v32, 1.0, vcc
	s_addk_i32 s30, 0x4000
	v_lshl_add_u64 v[152:153], v[18:19], 0, v[52:53]
	v_or3_b32 v156, v156, s55, v16
	v_mov_b64_e32 v[62:63], v[14:15]
	v_mov_b64_e32 v[46:47], v[14:15]
	v_mov_b64_e32 v[30:31], v[14:15]
	v_add_u32_e32 v216, s14, v89
	v_add_u32_e32 v217, s14, v90
	v_add_u32_e32 v218, s14, v91
	v_add_u32_e32 v175, s30, v92
	v_mov_b64_e32 v[60:61], v[12:13]
	v_mov_b64_e32 v[58:59], v[10:11]
	v_mov_b64_e32 v[56:57], v[8:9]
	v_mov_b64_e32 v[54:55], v[6:7]
	v_mov_b64_e32 v[52:53], v[4:5]
	v_mov_b64_e32 v[50:51], v[2:3]
	v_mov_b64_e32 v[48:49], v[0:1]
	v_mov_b64_e32 v[44:45], v[12:13]
	v_mov_b64_e32 v[42:43], v[10:11]
	v_mov_b64_e32 v[40:41], v[8:9]
	v_mov_b64_e32 v[38:39], v[6:7]
	v_mov_b64_e32 v[36:37], v[4:5]
	v_mov_b64_e32 v[34:35], v[2:3]
	v_mov_b64_e32 v[32:33], v[0:1]
	v_mov_b64_e32 v[28:29], v[12:13]
	v_mov_b64_e32 v[26:27], v[10:11]
	v_mov_b64_e32 v[24:25], v[8:9]
	v_mov_b64_e32 v[22:23], v[6:7]
	v_mov_b64_e32 v[20:21], v[4:5]
	v_mov_b64_e32 v[18:19], v[2:3]
	v_mov_b64_e32 v[16:17], v[0:1]
	s_waitcnt vmcnt(2)
	ds_write_b128 v216, v[70:73]
	s_waitcnt vmcnt(1)
	ds_write_b128 v217, v[74:77]
	s_waitcnt vmcnt(0)
	ds_write_b128 v218, v[78:81]
	s_waitcnt lgkmcnt(0)
	s_barrier
